# gateup: LN1 prologue hand-rewritten with all loads hoisted; gateup (rt,cgp) remapped so an XCD shares weight columns
# speedup vs baseline: 1.0083x; 1.0083x over previous
.LBB0_1056:
	v_mov_b32_e32 v146, v0
	s_add_u32 s18, s68, 0x10000000
	s_addc_u32 s19, s69, 0
	v_readfirstlane_b32 s0, v146
	s_ashr_i32 s8, s0, 8
	s_add_i32 s16, s12, 0xffffff80
	s_and_b32 s10, s16, 7
	s_bfe_u32 s11, s16, 0x10003
	s_lshl_b32 s10, s10, 1
	s_or_b32 s10, s10, s11
	s_lshr_b32 s11, s16, 4
	s_lshl_b32 s10, s10, 3
	s_or_b32 s16, s10, s11
	s_ashr_i32 s6, s0, 6
	s_ashr_i32 s9, s8, 31
	s_lshr_b32 s7, s16, 3
	s_and_b32 s13, s6, 3
	s_lshl_b64 s[0:1], s[8:9], 18
	s_add_u32 s0, s88, s0
	s_addc_u32 s1, s89, s1
	s_lshl_b32 s15, s13, 9
	s_add_u32 s0, s0, s15
	s_mul_i32 s3, s7, 0x160
	s_mul_i32 s10, s7, 48
	s_mul_i32 s2, s7, 11
	s_addc_u32 s1, s1, 0
	s_and_b32 s9, s3, 0x7fffff00
	s_and_b32 s10, s10, 0x70
	s_or_b32 s27, s10, s9
	s_add_i32 s9, s2, 1
	s_lshl_b32 s11, s9, 5
	s_lshl_b32 s9, s9, 4
	s_and_b32 s11, s11, 0x7fffff00
	s_and_b32 s9, s9, 0x70
	s_or_b32 s17, s9, s11
	s_add_i32 s9, s2, 2
	s_lshl_b32 s11, s9, 5
	s_lshl_b32 s9, s9, 4
	s_and_b32 s11, s11, 0x7fffff00
	s_and_b32 s9, s9, 0x70
	s_or_b32 s28, s9, s11
	s_add_i32 s9, s2, 3
	s_lshl_b32 s11, s9, 5
	s_lshl_b32 s9, s9, 4
	s_and_b32 s11, s11, 0x7fffff00
	s_and_b32 s9, s9, 0x70
	s_or_b32 s29, s9, s11
	s_add_i32 s9, s2, 4
	s_lshl_b32 s11, s9, 5
	s_lshl_b32 s9, s9, 4
	s_and_b32 s11, s11, 0x7fffff00
	s_and_b32 s9, s9, 0x70
	s_or_b32 s35, s9, s11
	s_add_i32 s9, s2, 5
	s_lshl_b32 s11, s9, 5
	s_lshl_b32 s9, s9, 4
	s_and_b32 s11, s11, 0x7fffff00
	s_and_b32 s9, s9, 0x70
	s_or_b32 s38, s9, s11
	s_add_i32 s9, s2, 6
	s_lshl_b32 s11, s9, 5
	s_lshl_b32 s9, s9, 4
	s_and_b32 s11, s11, 0x7fffff00
	s_and_b32 s9, s9, 0x70
	s_or_b32 s39, s9, s11
	s_add_i32 s9, s2, 7
	s_addk_i32 s3, 0x100
	s_lshl_b32 s11, s9, 5
	s_lshl_b32 s9, s9, 4
	s_and_b32 s3, s3, 0x7fffff00
	s_and_b32 s11, s11, 0x7fffff00
	s_and_b32 s9, s9, 0x70
	s_or_b32 s41, s10, s3
	s_add_i32 s3, s2, 9
	s_or_b32 s40, s9, s11
	s_lshl_b32 s9, s3, 5
	s_lshl_b32 s3, s3, 4
	s_and_b32 s9, s9, 0x7fffff00
	s_and_b32 s3, s3, 0x70
	s_add_i32 s2, s2, 10
	s_or_b32 s42, s3, s9
	s_lshl_b32 s3, s2, 5
	s_lshl_b32 s2, s2, 4
	s_and_b32 s3, s3, 0x7fffff00
	s_and_b32 s2, s2, 0x70
	s_or_b32 s43, s2, s3
	s_lshl_b32 s2, s16, 4
	s_lshl_b32 s26, s6, 1
	s_and_b32 s9, s2, 0x70
	s_cmp_lt_u32 s16, 8
	s_cselect_b64 s[2:3], -1, 0
	s_add_i32 s10, s26, s9
	s_ashr_i32 s11, s10, 31
	s_lshl_b64 s[22:23], s[10:11], 12
	v_and_b32_e32 v1, 63, v146
	v_mov_b32_e32 v107, 0
	s_add_u32 s30, s18, s22
	s_addc_u32 s31, s19, s23
	v_lshlrev_b32_e32 v130, 4, v1
	v_mov_b32_e32 v131, v107
	s_waitcnt lgkmcnt(0)
	v_lshl_add_u64 v[2:3], s[30:31], 0, v[130:131]
	s_brev_b32 s11, 32
	v_add_co_u32_e32 v4, vcc, s11, v2
	s_mov_b64 s[30:31], 0x4000000
	s_nop 0
	v_addc_co_u32_e32 v5, vcc, 0, v3, vcc
	global_load_dwordx4 v[102:105], v[4:5], off
	v_lshl_add_u64 v[2:3], v[2:3], 0, s[30:31]
	global_load_dwordx4 v[98:101], v[2:3], off offset:1024
	global_load_dwordx4 v[94:97], v[2:3], off offset:2048
	global_load_dwordx4 v[90:93], v[2:3], off offset:3072
	v_and_b32_e32 v147, 15, v146
	v_and_b32_e32 v106, 48, v146
	v_or_b32_e32 v2, s17, v147
	v_mov_b32_e32 v3, v107
	v_lshl_add_u64 v[4:5], s[0:1], 0, v[106:107]
	v_lshlrev_b64 v[2:3], 11, v[2:3]
	v_lshl_add_u64 v[110:111], v[4:5], 0, v[2:3]
	v_or_b32_e32 v2, s28, v147
	v_mov_b32_e32 v3, v107
	v_lshlrev_b64 v[2:3], 11, v[2:3]
	v_lshl_add_u64 v[112:113], v[4:5], 0, v[2:3]
	v_or_b32_e32 v2, s29, v147
	v_mov_b32_e32 v3, v107
	v_lshlrev_b64 v[2:3], 11, v[2:3]
	v_lshl_add_u64 v[114:115], v[4:5], 0, v[2:3]
	v_or_b32_e32 v2, s35, v147
	v_mov_b32_e32 v3, v107
	v_lshlrev_b64 v[2:3], 11, v[2:3]
	v_lshl_add_u64 v[116:117], v[4:5], 0, v[2:3]
	v_or_b32_e32 v2, s38, v147
	v_mov_b32_e32 v3, v107
	v_lshlrev_b64 v[2:3], 11, v[2:3]
	v_lshl_add_u64 v[118:119], v[4:5], 0, v[2:3]
	v_or_b32_e32 v2, s39, v147
	v_mov_b32_e32 v3, v107
	v_lshlrev_b64 v[2:3], 11, v[2:3]
	v_lshl_add_u64 v[120:121], v[4:5], 0, v[2:3]
	v_or_b32_e32 v2, s40, v147
	v_mov_b32_e32 v3, v107
	v_lshlrev_b64 v[2:3], 11, v[2:3]
	v_mbcnt_hi_u32_b32 v74, -1, v215
	v_lshl_add_u64 v[122:123], v[4:5], 0, v[2:3]
	v_or_b32_e32 v2, s41, v147
	v_mov_b32_e32 v3, v107
	v_and_b32_e32 v66, 64, v74
	v_lshlrev_b64 v[2:3], 11, v[2:3]
	v_add_u32_e32 v75, 64, v66
	v_xor_b32_e32 v66, 1, v74
	v_lshl_add_u64 v[124:125], v[4:5], 0, v[2:3]
	v_or_b32_e32 v2, s42, v147
	v_mov_b32_e32 v3, v107
	v_cmp_lt_i32_e32 vcc, v66, v75
	v_lshlrev_b64 v[2:3], 11, v[2:3]
	v_mov_b32_e32 v7, v107
	v_cndmask_b32_e32 v66, v74, v66, vcc
	v_lshl_add_u64 v[126:127], v[4:5], 0, v[2:3]
	v_mov_b32_e32 v3, v107
	v_lshlrev_b32_e32 v107, 2, v66
	v_or_b32_e32 v6, s27, v147
	v_lshlrev_b64 v[6:7], 11, v[6:7]
	v_or_b32_e32 v2, s43, v147
	v_lshl_add_u64 v[108:109], v[4:5], 0, v[6:7]
	v_lshlrev_b64 v[2:3], 11, v[2:3]
	v_lshl_add_u64 v[128:129], v[4:5], 0, v[2:3]
	global_load_dwordx4 v[34:37], v[108:109], off
	global_load_dwordx4 v[2:5], v[108:109], off offset:64
	global_load_dwordx4 v[38:41], v[110:111], off
	global_load_dwordx4 v[6:9], v[110:111], off offset:64
	global_load_dwordx4 v[42:45], v[112:113], off
	global_load_dwordx4 v[10:13], v[112:113], off offset:64
	global_load_dwordx4 v[46:49], v[114:115], off
	global_load_dwordx4 v[14:17], v[114:115], off offset:64
	global_load_dwordx4 v[50:53], v[116:117], off
	global_load_dwordx4 v[18:21], v[116:117], off offset:64
	global_load_dwordx4 v[54:57], v[118:119], off
	global_load_dwordx4 v[22:25], v[118:119], off offset:64
	global_load_dwordx4 v[58:61], v[120:121], off
	global_load_dwordx4 v[26:29], v[120:121], off offset:64
	global_load_dwordx4 v[62:65], v[122:123], off
	global_load_dwordx4 v[30:33], v[122:123], off offset:64
	v_readlane_b32 s40, v245, 18
	v_readlane_b32 s41, v245, 19
	v_readlane_b32 s42, v245, 20
	v_readlane_b32 s43, v245, 21
	s_mov_b32 s0, 0xf800000
	s_add_u32 s22, s4, s22
	v_lshlrev_b32_e32 v157, 2, v1
	s_addc_u32 s23, s5, s23
	s_cmp_gt_u32 s16, 7
	v_readlane_b32 s44, v245, 22
	v_readlane_b32 s45, v245, 23
	v_readlane_b32 s46, v245, 24
	v_readlane_b32 s47, v245, 25
	v_readlane_b32 s48, v245, 26
	v_readlane_b32 s49, v245, 27
	v_readlane_b32 s50, v245, 28
	v_readlane_b32 s51, v245, 29
	v_readlane_b32 s52, v245, 30
	v_readlane_b32 s53, v245, 31
	v_readlane_b32 s54, v245, 32
	global_load_dwordx4 v[74:77], v[124:125], off
	global_load_dwordx4 v[66:69], v[124:125], off offset:64
	global_load_dwordx4 v[78:81], v[126:127], off
	global_load_dwordx4 v[70:73], v[126:127], off offset:64
	global_load_dwordx4 v[86:89], v[128:129], off
	global_load_dwordx4 v[82:85], v[128:129], off offset:64
	s_lshl_b32 s0, s10, 12
	s_add_u32 s16, s18, s0
	s_addc_u32 s17, s19, 0
	s_add_u32 s16, s16, 0x4001000
	s_addc_u32 s17, s17, 0
	global_load_dwordx4 v[174:177], v130, s[16:17]
	global_load_dwordx4 v[178:181], v130, s[16:17] offset:1024
	global_load_dwordx4 v[182:185], v130, s[16:17] offset:2048
	global_load_dwordx4 v[186:189], v130, s[16:17] offset:3072
	global_load_dwordx4 v[190:193], v130, s[40:41]
	global_load_dwordx4 v[194:197], v130, s[40:41] offset:1024
	global_load_dwordx4 v[198:201], v130, s[40:41] offset:2048
	global_load_dwordx4 v[202:205], v130, s[40:41] offset:3072
	global_load_dwordx4 v[206:209], v130, s[42:43]
	global_load_dwordx4 v[210:213], v130, s[42:43] offset:1024
	global_load_dwordx4 v[216:219], v130, s[42:43] offset:2048
	global_load_dwordx4 v[220:223], v130, s[42:43] offset:3072
	s_add_i32 s0, s10, 8
	s_mul_i32 s0, s0, 0x6000
	s_add_u32 s0, s70, s0
	s_addc_u32 s1, s71, 0
	s_add_u32 s16, s0, 0x4000
	s_addc_u32 s17, s1, 0
	s_add_u32 s10, s0, 0x3000
	s_addc_u32 s11, s1, 0
	global_load_dwordx4 v[224:227], v130, s[16:17]
	global_load_dwordx4 v[228:231], v130, s[16:17] offset:1024
	global_load_dwordx4 v[232:235], v130, s[16:17] offset:2048
	global_load_dwordx4 v[236:239], v130, s[16:17] offset:3072
	global_load_dwordx4 v[148:151], v130, s[10:11]
	global_load_dwordx4 v[152:155], v130, s[10:11] offset:1024
	global_load_dwordx4 v[156:159], v130, s[10:11] offset:2048
	global_load_dwordx4 v[160:163], v130, s[10:11] offset:3072
	v_xor_b32_e32 v132, 1, v1
	v_xor_b32_e32 v133, 2, v1
	v_xor_b32_e32 v134, 4, v1
	v_xor_b32_e32 v135, 8, v1
	v_xor_b32_e32 v136, 16, v1
	v_xor_b32_e32 v137, 32, v1
	v_lshlrev_b32_e32 v132, 2, v132
	v_lshlrev_b32_e32 v133, 2, v133
	v_lshlrev_b32_e32 v134, 2, v134
	v_lshlrev_b32_e32 v135, 2, v135
	v_lshlrev_b32_e32 v136, 2, v136
	v_lshlrev_b32_e32 v137, 2, v137
	s_mul_i32 s27, s6, 0x1020
	s_add_i32 s27, s27, 0x18000
	v_lshl_add_u32 v144, v1, 3, s27
	s_waitcnt vmcnt(16)
	v_add_f32_e32 v140, v102, v103
	v_add_f32_e32 v141, v104, v105
	v_add_f32_e32 v138, v140, v141
	v_add_f32_e32 v140, v98, v99
	v_add_f32_e32 v141, v100, v101
	v_add_f32_e32 v140, v140, v141
	v_add_f32_e32 v138, v138, v140
	v_add_f32_e32 v140, v94, v95
	v_add_f32_e32 v141, v96, v97
	v_add_f32_e32 v140, v140, v141
	v_add_f32_e32 v138, v138, v140
	v_add_f32_e32 v140, v90, v91
	v_add_f32_e32 v141, v92, v93
	v_add_f32_e32 v140, v140, v141
	v_add_f32_e32 v138, v138, v140
	v_add_f32_e32 v140, v174, v175
	v_add_f32_e32 v141, v176, v177
	v_add_f32_e32 v139, v140, v141
	v_add_f32_e32 v140, v178, v179
	v_add_f32_e32 v141, v180, v181
	v_add_f32_e32 v140, v140, v141
	v_add_f32_e32 v139, v139, v140
	v_add_f32_e32 v140, v182, v183
	v_add_f32_e32 v141, v184, v185
	v_add_f32_e32 v140, v140, v141
	v_add_f32_e32 v139, v139, v140
	v_add_f32_e32 v140, v186, v187
	v_add_f32_e32 v141, v188, v189
	v_add_f32_e32 v140, v140, v141
	v_add_f32_e32 v139, v139, v140
	ds_bpermute_b32 v140, v132, v138
	ds_bpermute_b32 v141, v132, v139
	s_waitcnt lgkmcnt(0)
	v_add_f32_e32 v138, v138, v140
	v_add_f32_e32 v139, v139, v141
	ds_bpermute_b32 v140, v133, v138
	ds_bpermute_b32 v141, v133, v139
	s_waitcnt lgkmcnt(0)
	v_add_f32_e32 v138, v138, v140
	v_add_f32_e32 v139, v139, v141
	ds_bpermute_b32 v140, v134, v138
	ds_bpermute_b32 v141, v134, v139
	s_waitcnt lgkmcnt(0)
	v_add_f32_e32 v138, v138, v140
	v_add_f32_e32 v139, v139, v141
	ds_bpermute_b32 v140, v135, v138
	ds_bpermute_b32 v141, v135, v139
	s_waitcnt lgkmcnt(0)
	v_add_f32_e32 v138, v138, v140
	v_add_f32_e32 v139, v139, v141
	ds_bpermute_b32 v140, v136, v138
	ds_bpermute_b32 v141, v136, v139
	s_waitcnt lgkmcnt(0)
	v_add_f32_e32 v138, v138, v140
	v_add_f32_e32 v139, v139, v141
	ds_bpermute_b32 v140, v137, v138
	ds_bpermute_b32 v141, v137, v139
	s_waitcnt lgkmcnt(0)
	v_add_f32_e32 v138, v138, v140
	v_add_f32_e32 v139, v139, v141
	v_fmac_f32_e32 v102, 0xba800000, v138
	v_fmac_f32_e32 v103, 0xba800000, v138
	v_fmac_f32_e32 v104, 0xba800000, v138
	v_fmac_f32_e32 v105, 0xba800000, v138
	v_fmac_f32_e32 v98, 0xba800000, v138
	v_fmac_f32_e32 v99, 0xba800000, v138
	v_fmac_f32_e32 v100, 0xba800000, v138
	v_fmac_f32_e32 v101, 0xba800000, v138
	v_fmac_f32_e32 v94, 0xba800000, v138
	v_fmac_f32_e32 v95, 0xba800000, v138
	v_fmac_f32_e32 v96, 0xba800000, v138
	v_fmac_f32_e32 v97, 0xba800000, v138
	v_fmac_f32_e32 v90, 0xba800000, v138
	v_fmac_f32_e32 v91, 0xba800000, v138
	v_fmac_f32_e32 v92, 0xba800000, v138
	v_fmac_f32_e32 v93, 0xba800000, v138
	v_fmac_f32_e32 v174, 0xba800000, v139
	v_fmac_f32_e32 v175, 0xba800000, v139
	v_fmac_f32_e32 v176, 0xba800000, v139
	v_fmac_f32_e32 v177, 0xba800000, v139
	v_fmac_f32_e32 v178, 0xba800000, v139
	v_fmac_f32_e32 v179, 0xba800000, v139
	v_fmac_f32_e32 v180, 0xba800000, v139
	v_fmac_f32_e32 v181, 0xba800000, v139
	v_fmac_f32_e32 v182, 0xba800000, v139
	v_fmac_f32_e32 v183, 0xba800000, v139
	v_fmac_f32_e32 v184, 0xba800000, v139
	v_fmac_f32_e32 v185, 0xba800000, v139
	v_fmac_f32_e32 v186, 0xba800000, v139
	v_fmac_f32_e32 v187, 0xba800000, v139
	v_fmac_f32_e32 v188, 0xba800000, v139
	v_fmac_f32_e32 v189, 0xba800000, v139
	v_mul_f32_e32 v140, v102, v102
	v_fmac_f32_e32 v140, v103, v103
	v_mul_f32_e32 v141, v104, v104
	v_fmac_f32_e32 v141, v105, v105
	v_add_f32_e32 v138, v140, v141
	v_mul_f32_e32 v140, v98, v98
	v_fmac_f32_e32 v140, v99, v99
	v_mul_f32_e32 v141, v100, v100
	v_fmac_f32_e32 v141, v101, v101
	v_add_f32_e32 v140, v140, v141
	v_add_f32_e32 v138, v138, v140
	v_mul_f32_e32 v140, v94, v94
	v_fmac_f32_e32 v140, v95, v95
	v_mul_f32_e32 v141, v96, v96
	v_fmac_f32_e32 v141, v97, v97
	v_add_f32_e32 v140, v140, v141
	v_add_f32_e32 v138, v138, v140
	v_mul_f32_e32 v140, v90, v90
	v_fmac_f32_e32 v140, v91, v91
	v_mul_f32_e32 v141, v92, v92
	v_fmac_f32_e32 v141, v93, v93
	v_add_f32_e32 v140, v140, v141
	v_add_f32_e32 v138, v138, v140
	v_mul_f32_e32 v140, v174, v174
	v_fmac_f32_e32 v140, v175, v175
	v_mul_f32_e32 v141, v176, v176
	v_fmac_f32_e32 v141, v177, v177
	v_add_f32_e32 v139, v140, v141
	v_mul_f32_e32 v140, v178, v178
	v_fmac_f32_e32 v140, v179, v179
	v_mul_f32_e32 v141, v180, v180
	v_fmac_f32_e32 v141, v181, v181
	v_add_f32_e32 v140, v140, v141
	v_add_f32_e32 v139, v139, v140
	v_mul_f32_e32 v140, v182, v182
	v_fmac_f32_e32 v140, v183, v183
	v_mul_f32_e32 v141, v184, v184
	v_fmac_f32_e32 v141, v185, v185
	v_add_f32_e32 v140, v140, v141
	v_add_f32_e32 v139, v139, v140
	v_mul_f32_e32 v140, v186, v186
	v_fmac_f32_e32 v140, v187, v187
	v_mul_f32_e32 v141, v188, v188
	v_fmac_f32_e32 v141, v189, v189
	v_add_f32_e32 v140, v140, v141
	v_add_f32_e32 v139, v139, v140
	ds_bpermute_b32 v140, v132, v138
	ds_bpermute_b32 v141, v132, v139
	s_waitcnt lgkmcnt(0)
	v_add_f32_e32 v138, v138, v140
	v_add_f32_e32 v139, v139, v141
	ds_bpermute_b32 v140, v133, v138
	ds_bpermute_b32 v141, v133, v139
	s_waitcnt lgkmcnt(0)
	v_add_f32_e32 v138, v138, v140
	v_add_f32_e32 v139, v139, v141
	ds_bpermute_b32 v140, v134, v138
	ds_bpermute_b32 v141, v134, v139
	s_waitcnt lgkmcnt(0)
	v_add_f32_e32 v138, v138, v140
	v_add_f32_e32 v139, v139, v141
	ds_bpermute_b32 v140, v135, v138
	ds_bpermute_b32 v141, v135, v139
	s_waitcnt lgkmcnt(0)
	v_add_f32_e32 v138, v138, v140
	v_add_f32_e32 v139, v139, v141
	ds_bpermute_b32 v140, v136, v138
	ds_bpermute_b32 v141, v136, v139
	s_waitcnt lgkmcnt(0)
	v_add_f32_e32 v138, v138, v140
	v_add_f32_e32 v139, v139, v141
	ds_bpermute_b32 v140, v137, v138
	ds_bpermute_b32 v141, v137, v139
	s_waitcnt lgkmcnt(0)
	v_add_f32_e32 v138, v138, v140
	v_add_f32_e32 v139, v139, v141
	s_mov_b32 s27, 0xf800000
	v_mov_b32_e32 v165, 0x3727c5ac
	v_fmac_f32_e32 v165, 0x3a800000, v138
	v_mul_f32_e32 v164, 0x4f800000, v165
	v_cmp_gt_f32_e32 vcc, s27, v165
	s_nop 1
	v_cndmask_b32_e32 v164, v165, v164, vcc
	v_sqrt_f32_e32 v165, v164
	s_nop 0
	v_add_u32_e32 v166, -1, v165
	v_fma_f32 v167, -v166, v165, v164
	v_cmp_ge_f32_e64 s[0:1], 0, v167
	v_add_u32_e32 v167, 1, v165
	s_nop 0
	v_cndmask_b32_e64 v166, v165, v166, s[0:1]
	v_fma_f32 v165, -v167, v165, v164
	v_cmp_lt_f32_e64 s[0:1], 0, v165
	s_nop 1
	v_cndmask_b32_e64 v165, v166, v167, s[0:1]
	v_mul_f32_e32 v166, 0x37800000, v165
	v_cndmask_b32_e32 v165, v165, v166, vcc
	v_mov_b32_e32 v166, 0x260
	v_cmp_class_f32_e32 vcc, v164, v166
	s_nop 1
	v_cndmask_b32_e32 v164, v165, v164, vcc
	v_div_scale_f32 v165, s[0:1], v164, v164, 1.0
	v_rcp_f32_e32 v166, v165
	s_nop 0
	v_fma_f32 v167, -v165, v166, 1.0
	v_fmac_f32_e32 v166, v167, v166
	v_div_scale_f32 v167, vcc, 1.0, v164, 1.0
	v_mul_f32_e32 v168, v167, v166
	v_fma_f32 v169, -v165, v168, v167
	v_fmac_f32_e32 v168, v169, v166
	v_fma_f32 v165, -v165, v168, v167
	v_div_fmas_f32 v165, v165, v166, v168
	v_div_fixup_f32 v142, v165, v164, 1.0
	v_mov_b32_e32 v165, 0x3727c5ac
	v_fmac_f32_e32 v165, 0x3a800000, v139
	v_mul_f32_e32 v164, 0x4f800000, v165
	v_cmp_gt_f32_e32 vcc, s27, v165
	s_nop 1
	v_cndmask_b32_e32 v164, v165, v164, vcc
	v_sqrt_f32_e32 v165, v164
	s_nop 0
	v_add_u32_e32 v166, -1, v165
	v_fma_f32 v167, -v166, v165, v164
	v_cmp_ge_f32_e64 s[0:1], 0, v167
	v_add_u32_e32 v167, 1, v165
	s_nop 0
	v_cndmask_b32_e64 v166, v165, v166, s[0:1]
	v_fma_f32 v165, -v167, v165, v164
	v_cmp_lt_f32_e64 s[0:1], 0, v165
	s_nop 1
	v_cndmask_b32_e64 v165, v166, v167, s[0:1]
	v_mul_f32_e32 v166, 0x37800000, v165
	v_cndmask_b32_e32 v165, v165, v166, vcc
	v_mov_b32_e32 v166, 0x260
	v_cmp_class_f32_e32 vcc, v164, v166
	s_nop 1
	v_cndmask_b32_e32 v164, v165, v164, vcc
	v_div_scale_f32 v165, s[0:1], v164, v164, 1.0
	v_rcp_f32_e32 v166, v165
	s_nop 0
	v_fma_f32 v167, -v165, v166, 1.0
	v_fmac_f32_e32 v166, v167, v166
	v_div_scale_f32 v167, vcc, 1.0, v164, 1.0
	v_mul_f32_e32 v168, v167, v166
	v_fma_f32 v169, -v165, v168, v167
	v_fmac_f32_e32 v168, v169, v166
	v_fma_f32 v165, -v165, v168, v167
	v_div_fmas_f32 v165, v165, v166, v168
	v_div_fixup_f32 v143, v165, v164, 1.0
	s_waitcnt vmcnt(0)
	v_mul_f32_e32 v164, v102, v142
	v_mul_f32_e32 v165, v103, v142
	v_mul_f32_e32 v166, v104, v142
	v_mul_f32_e32 v167, v105, v142
	v_fma_f32 v164, v164, v190, v206
	v_fma_f32 v165, v165, v191, v207
	v_fma_f32 v166, v166, v192, v208
	v_fma_f32 v167, v167, v193, v209
	s_and_saveexec_b64 s[0:1], s[2:3]
	global_store_dwordx4 v130, v[164:167], s[22:23]
	s_mov_b64 exec, s[0:1]
	v_add_f32_e32 v168, 1.0, v224
	v_add_f32_e32 v169, 1.0, v225
	v_add_f32_e32 v170, 1.0, v226
	v_add_f32_e32 v171, 1.0, v227
	v_fma_f32 v168, v164, v168, v148
	v_fma_f32 v169, v165, v169, v149
	v_fma_f32 v170, v166, v170, v150
	v_fma_f32 v171, v167, v171, v151
	v_cvt_pk_bf16_f32 v172, v168, v169
	v_cvt_pk_bf16_f32 v173, v170, v171
	ds_write_b64 v144, v[172:173]
	v_mul_f32_e32 v164, v98, v142
	v_mul_f32_e32 v165, v99, v142
	v_mul_f32_e32 v166, v100, v142
	v_mul_f32_e32 v167, v101, v142
	v_fma_f32 v164, v164, v194, v210
	v_fma_f32 v165, v165, v195, v211
	v_fma_f32 v166, v166, v196, v212
	v_fma_f32 v167, v167, v197, v213
	s_and_saveexec_b64 s[0:1], s[2:3]
	global_store_dwordx4 v130, v[164:167], s[22:23] offset:1024
	s_mov_b64 exec, s[0:1]
	v_add_f32_e32 v168, 1.0, v228
	v_add_f32_e32 v169, 1.0, v229
	v_add_f32_e32 v170, 1.0, v230
	v_add_f32_e32 v171, 1.0, v231
	v_fma_f32 v168, v164, v168, v152
	v_fma_f32 v169, v165, v169, v153
	v_fma_f32 v170, v166, v170, v154
	v_fma_f32 v171, v167, v171, v155
	v_cvt_pk_bf16_f32 v172, v168, v169
	v_cvt_pk_bf16_f32 v173, v170, v171
	ds_write_b64 v144, v[172:173] offset:512
	v_mul_f32_e32 v164, v94, v142
	v_mul_f32_e32 v165, v95, v142
	v_mul_f32_e32 v166, v96, v142
	v_mul_f32_e32 v167, v97, v142
	v_fma_f32 v164, v164, v198, v216
	v_fma_f32 v165, v165, v199, v217
	v_fma_f32 v166, v166, v200, v218
	v_fma_f32 v167, v167, v201, v219
	s_and_saveexec_b64 s[0:1], s[2:3]
	global_store_dwordx4 v130, v[164:167], s[22:23] offset:2048
	s_mov_b64 exec, s[0:1]
	v_add_f32_e32 v168, 1.0, v232
	v_add_f32_e32 v169, 1.0, v233
	v_add_f32_e32 v170, 1.0, v234
	v_add_f32_e32 v171, 1.0, v235
	v_fma_f32 v168, v164, v168, v156
	v_fma_f32 v169, v165, v169, v157
	v_fma_f32 v170, v166, v170, v158
	v_fma_f32 v171, v167, v171, v159
	v_cvt_pk_bf16_f32 v172, v168, v169
	v_cvt_pk_bf16_f32 v173, v170, v171
	ds_write_b64 v144, v[172:173] offset:1024
	v_mul_f32_e32 v164, v90, v142
	v_mul_f32_e32 v165, v91, v142
	v_mul_f32_e32 v166, v92, v142
	v_mul_f32_e32 v167, v93, v142
	v_fma_f32 v164, v164, v202, v220
	v_fma_f32 v165, v165, v203, v221
	v_fma_f32 v166, v166, v204, v222
	v_fma_f32 v167, v167, v205, v223
	s_and_saveexec_b64 s[0:1], s[2:3]
	global_store_dwordx4 v130, v[164:167], s[22:23] offset:3072
	s_mov_b64 exec, s[0:1]
	v_add_f32_e32 v168, 1.0, v236
	v_add_f32_e32 v169, 1.0, v237
	v_add_f32_e32 v170, 1.0, v238
	v_add_f32_e32 v171, 1.0, v239
	v_fma_f32 v168, v164, v168, v160
	v_fma_f32 v169, v165, v169, v161
	v_fma_f32 v170, v166, v170, v162
	v_fma_f32 v171, v167, v171, v163
	v_cvt_pk_bf16_f32 v172, v168, v169
	v_cvt_pk_bf16_f32 v173, v170, v171
	ds_write_b64 v144, v[172:173] offset:1536
	s_add_u32 s16, s16, 0x6000
	s_addc_u32 s17, s17, 0
	s_add_u32 s10, s10, 0x6000
	s_addc_u32 s11, s11, 0
	s_add_u32 s22, s22, 0x1000
	s_addc_u32 s23, s23, 0
	s_nop 0
	global_load_dwordx4 v[224:227], v130, s[16:17]
	global_load_dwordx4 v[228:231], v130, s[16:17] offset:1024
	global_load_dwordx4 v[232:235], v130, s[16:17] offset:2048
	global_load_dwordx4 v[236:239], v130, s[16:17] offset:3072
	global_load_dwordx4 v[148:151], v130, s[10:11]
	global_load_dwordx4 v[152:155], v130, s[10:11] offset:1024
	global_load_dwordx4 v[156:159], v130, s[10:11] offset:2048
	global_load_dwordx4 v[160:163], v130, s[10:11] offset:3072
	v_mul_f32_e32 v164, v174, v143
	v_mul_f32_e32 v165, v175, v143
	v_mul_f32_e32 v166, v176, v143
	v_mul_f32_e32 v167, v177, v143
	v_fma_f32 v164, v164, v190, v206
	v_fma_f32 v165, v165, v191, v207
	v_fma_f32 v166, v166, v192, v208
	v_fma_f32 v167, v167, v193, v209
	s_and_saveexec_b64 s[0:1], s[2:3]
	global_store_dwordx4 v130, v[164:167], s[22:23]
	s_mov_b64 exec, s[0:1]
	s_waitcnt vmcnt(0)
	v_add_f32_e32 v168, 1.0, v224
	v_add_f32_e32 v169, 1.0, v225
	v_add_f32_e32 v170, 1.0, v226
	v_add_f32_e32 v171, 1.0, v227
	v_fma_f32 v168, v164, v168, v148
	v_fma_f32 v169, v165, v169, v149
	v_fma_f32 v170, v166, v170, v150
	v_fma_f32 v171, v167, v171, v151
	v_cvt_pk_bf16_f32 v172, v168, v169
	v_cvt_pk_bf16_f32 v173, v170, v171
	ds_write_b64 v144, v[172:173] offset:2064
	v_mul_f32_e32 v164, v178, v143
	v_mul_f32_e32 v165, v179, v143
	v_mul_f32_e32 v166, v180, v143
	v_mul_f32_e32 v167, v181, v143
	v_fma_f32 v164, v164, v194, v210
	v_fma_f32 v165, v165, v195, v211
	v_fma_f32 v166, v166, v196, v212
	v_fma_f32 v167, v167, v197, v213
	s_and_saveexec_b64 s[0:1], s[2:3]
	global_store_dwordx4 v130, v[164:167], s[22:23] offset:1024
	s_mov_b64 exec, s[0:1]
	v_add_f32_e32 v168, 1.0, v228
	v_add_f32_e32 v169, 1.0, v229
	v_add_f32_e32 v170, 1.0, v230
	v_add_f32_e32 v171, 1.0, v231
	v_fma_f32 v168, v164, v168, v152
	v_fma_f32 v169, v165, v169, v153
	v_fma_f32 v170, v166, v170, v154
	v_fma_f32 v171, v167, v171, v155
	v_cvt_pk_bf16_f32 v172, v168, v169
	v_cvt_pk_bf16_f32 v173, v170, v171
	ds_write_b64 v144, v[172:173] offset:2576
	v_mul_f32_e32 v164, v182, v143
	v_mul_f32_e32 v165, v183, v143
	v_mul_f32_e32 v166, v184, v143
	v_mul_f32_e32 v167, v185, v143
	v_fma_f32 v164, v164, v198, v216
	v_fma_f32 v165, v165, v199, v217
	v_fma_f32 v166, v166, v200, v218
	v_fma_f32 v167, v167, v201, v219
	s_and_saveexec_b64 s[0:1], s[2:3]
	global_store_dwordx4 v130, v[164:167], s[22:23] offset:2048
	s_mov_b64 exec, s[0:1]
	v_add_f32_e32 v168, 1.0, v232
	v_add_f32_e32 v169, 1.0, v233
	v_add_f32_e32 v170, 1.0, v234
	v_add_f32_e32 v171, 1.0, v235
	v_fma_f32 v168, v164, v168, v156
	v_fma_f32 v169, v165, v169, v157
	v_fma_f32 v170, v166, v170, v158
	v_fma_f32 v171, v167, v171, v159
	v_cvt_pk_bf16_f32 v172, v168, v169
	v_cvt_pk_bf16_f32 v173, v170, v171
	ds_write_b64 v144, v[172:173] offset:3088
	v_mul_f32_e32 v164, v186, v143
	v_mul_f32_e32 v165, v187, v143
	v_mul_f32_e32 v166, v188, v143
	v_mul_f32_e32 v167, v189, v143
	v_fma_f32 v164, v164, v202, v220
	v_fma_f32 v165, v165, v203, v221
	v_fma_f32 v166, v166, v204, v222
	v_fma_f32 v167, v167, v205, v223
	s_and_saveexec_b64 s[0:1], s[2:3]
	global_store_dwordx4 v130, v[164:167], s[22:23] offset:3072
	s_mov_b64 exec, s[0:1]
	v_add_f32_e32 v168, 1.0, v236
	v_add_f32_e32 v169, 1.0, v237
	v_add_f32_e32 v170, 1.0, v238
	v_add_f32_e32 v171, 1.0, v239
	v_fma_f32 v168, v164, v168, v160
	v_fma_f32 v169, v165, v169, v161
	v_fma_f32 v170, v166, v170, v162
	v_fma_f32 v171, v167, v171, v163
	v_cvt_pk_bf16_f32 v172, v168, v169
	v_cvt_pk_bf16_f32 v173, v170, v171
	ds_write_b64 v144, v[172:173] offset:3600
	s_add_i32 s0, 0, 0x18000
	s_movk_i32 s1, 0x810
	v_mov_b32_e32 v103, s0
	s_nop 0
	v_mad_u32_u24 v103, v147, s1, v103
	v_add3_u32 v103, v103, v106, s15
	s_mul_i32 s0, s13, 22
	s_mul_i32 s1, s8, 11
	s_add_i32 s0, s0, s1
	s_lshl_b32 s0, s0, 10
	s_add_i32 s0, s0, 0
	s_waitcnt vmcnt(0) lgkmcnt(0)
	s_cmp_gt_i32 s6, 10
	s_barrier
	ds_read_b128 v[90:93], v103
	ds_read_b128 v[94:97], v103 offset:64
	s_waitcnt lgkmcnt(1)
	v_mfma_f32_16x16x32_bf16 v[34:37], v[34:37], v[90:93], 0
	ds_read_b128 v[98:101], v103 offset:128
	v_mfma_f32_16x16x32_bf16 v[38:41], v[38:41], v[90:93], 0
	v_mfma_f32_16x16x32_bf16 v[42:45], v[42:45], v[90:93], 0
	v_mfma_f32_16x16x32_bf16 v[46:49], v[46:49], v[90:93], 0
	v_mfma_f32_16x16x32_bf16 v[50:53], v[50:53], v[90:93], 0
	v_mfma_f32_16x16x32_bf16 v[54:57], v[54:57], v[90:93], 0
	v_mfma_f32_16x16x32_bf16 v[58:61], v[58:61], v[90:93], 0
	v_mfma_f32_16x16x32_bf16 v[62:65], v[62:65], v[90:93], 0
	v_mfma_f32_16x16x32_bf16 v[74:77], v[74:77], v[90:93], 0
	v_mfma_f32_16x16x32_bf16 v[78:81], v[78:81], v[90:93], 0
	v_mfma_f32_16x16x32_bf16 v[86:89], v[86:89], v[90:93], 0
	global_load_dwordx4 v[90:93], v[108:109], off offset:128
	s_waitcnt lgkmcnt(1)
	v_mfma_f32_16x16x32_bf16 v[2:5], v[2:5], v[94:97], v[34:37]
	s_nop 2
	global_load_dwordx4 v[34:37], v[110:111], off offset:128
	v_mfma_f32_16x16x32_bf16 v[6:9], v[6:9], v[94:97], v[38:41]
	s_nop 2
	global_load_dwordx4 v[38:41], v[112:113], off offset:128
	v_mfma_f32_16x16x32_bf16 v[10:13], v[10:13], v[94:97], v[42:45]
	s_nop 2
	global_load_dwordx4 v[42:45], v[114:115], off offset:128
	v_mfma_f32_16x16x32_bf16 v[14:17], v[14:17], v[94:97], v[46:49]
	s_nop 2
	global_load_dwordx4 v[46:49], v[116:117], off offset:128
	v_mfma_f32_16x16x32_bf16 v[18:21], v[18:21], v[94:97], v[50:53]
	s_nop 2
	global_load_dwordx4 v[50:53], v[118:119], off offset:128
	v_mfma_f32_16x16x32_bf16 v[22:25], v[22:25], v[94:97], v[54:57]
	s_nop 2
	global_load_dwordx4 v[54:57], v[120:121], off offset:128
	v_mfma_f32_16x16x32_bf16 v[26:29], v[26:29], v[94:97], v[58:61]
	s_nop 2
	global_load_dwordx4 v[58:61], v[122:123], off offset:128
	v_mfma_f32_16x16x32_bf16 v[30:33], v[30:33], v[94:97], v[62:65]
	s_nop 2
	global_load_dwordx4 v[62:65], v[124:125], off offset:128
	v_mfma_f32_16x16x32_bf16 v[66:69], v[66:69], v[94:97], v[74:77]
	s_nop 2
	global_load_dwordx4 v[74:77], v[126:127], off offset:128
	v_mfma_f32_16x16x32_bf16 v[70:73], v[70:73], v[94:97], v[78:81]
	s_nop 2
	global_load_dwordx4 v[78:81], v[128:129], off offset:128
	v_mfma_f32_16x16x32_bf16 v[82:85], v[82:85], v[94:97], v[86:89]
	ds_read_b128 v[94:97], v103 offset:192
	s_nop 1
	global_load_dwordx4 v[86:89], v[108:109], off offset:192
	s_waitcnt vmcnt(11) lgkmcnt(1)
	v_mfma_f32_16x16x32_bf16 v[2:5], v[90:93], v[98:101], v[2:5]
	global_load_dwordx4 v[90:93], v[110:111], off offset:192
	s_waitcnt vmcnt(11)
	v_mfma_f32_16x16x32_bf16 v[6:9], v[34:37], v[98:101], v[6:9]
	global_load_dwordx4 v[34:37], v[112:113], off offset:192
	s_waitcnt vmcnt(11)
	v_mfma_f32_16x16x32_bf16 v[10:13], v[38:41], v[98:101], v[10:13]
	global_load_dwordx4 v[38:41], v[114:115], off offset:192
	s_waitcnt vmcnt(11)
	v_mfma_f32_16x16x32_bf16 v[14:17], v[42:45], v[98:101], v[14:17]
	global_load_dwordx4 v[42:45], v[116:117], off offset:192
	s_waitcnt vmcnt(11)
	v_mfma_f32_16x16x32_bf16 v[18:21], v[46:49], v[98:101], v[18:21]
	global_load_dwordx4 v[46:49], v[118:119], off offset:192
	s_waitcnt vmcnt(11)
	v_mfma_f32_16x16x32_bf16 v[22:25], v[50:53], v[98:101], v[22:25]
	global_load_dwordx4 v[50:53], v[120:121], off offset:192
	s_waitcnt vmcnt(11)
	v_mfma_f32_16x16x32_bf16 v[26:29], v[54:57], v[98:101], v[26:29]
	global_load_dwordx4 v[54:57], v[122:123], off offset:192
	s_waitcnt vmcnt(11)
	v_mfma_f32_16x16x32_bf16 v[30:33], v[58:61], v[98:101], v[30:33]
	global_load_dwordx4 v[58:61], v[124:125], off offset:192
	s_waitcnt vmcnt(11)
	v_mfma_f32_16x16x32_bf16 v[62:65], v[62:65], v[98:101], v[66:69]
	s_nop 2
	global_load_dwordx4 v[66:69], v[126:127], off offset:192
	s_waitcnt vmcnt(11)
	v_mfma_f32_16x16x32_bf16 v[70:73], v[74:77], v[98:101], v[70:73]
	global_load_dwordx4 v[74:77], v[128:129], off offset:192
	s_waitcnt vmcnt(11)
	v_mfma_f32_16x16x32_bf16 v[78:81], v[78:81], v[98:101], v[82:85]
	ds_read_b128 v[98:101], v103 offset:256
	s_nop 1
	global_load_dwordx4 v[82:85], v[108:109], off offset:256
	s_waitcnt vmcnt(11) lgkmcnt(1)
	v_mfma_f32_16x16x32_bf16 v[2:5], v[86:89], v[94:97], v[2:5]
	global_load_dwordx4 v[86:89], v[110:111], off offset:256
	s_waitcnt vmcnt(11)
	v_mfma_f32_16x16x32_bf16 v[6:9], v[90:93], v[94:97], v[6:9]
	global_load_dwordx4 v[90:93], v[112:113], off offset:256
	s_waitcnt vmcnt(11)
	v_mfma_f32_16x16x32_bf16 v[10:13], v[34:37], v[94:97], v[10:13]
	global_load_dwordx4 v[34:37], v[114:115], off offset:256
	s_waitcnt vmcnt(11)
	v_mfma_f32_16x16x32_bf16 v[14:17], v[38:41], v[94:97], v[14:17]
	global_load_dwordx4 v[38:41], v[116:117], off offset:256
	s_waitcnt vmcnt(11)
	v_mfma_f32_16x16x32_bf16 v[18:21], v[42:45], v[94:97], v[18:21]
	global_load_dwordx4 v[42:45], v[118:119], off offset:256
	s_waitcnt vmcnt(11)
	v_mfma_f32_16x16x32_bf16 v[22:25], v[46:49], v[94:97], v[22:25]
	global_load_dwordx4 v[46:49], v[120:121], off offset:256
	s_waitcnt vmcnt(11)
	v_mfma_f32_16x16x32_bf16 v[26:29], v[50:53], v[94:97], v[26:29]
	global_load_dwordx4 v[50:53], v[122:123], off offset:256
	s_waitcnt vmcnt(11)
	v_mfma_f32_16x16x32_bf16 v[30:33], v[54:57], v[94:97], v[30:33]
	global_load_dwordx4 v[54:57], v[124:125], off offset:256
	s_waitcnt vmcnt(11)
	v_mfma_f32_16x16x32_bf16 v[58:61], v[58:61], v[94:97], v[62:65]
	s_nop 2
	global_load_dwordx4 v[62:65], v[126:127], off offset:256
	s_waitcnt vmcnt(11)
	v_mfma_f32_16x16x32_bf16 v[66:69], v[66:69], v[94:97], v[70:73]
	s_nop 2
	global_load_dwordx4 v[70:73], v[128:129], off offset:256
	s_waitcnt vmcnt(11)
	v_mfma_f32_16x16x32_bf16 v[74:77], v[74:77], v[94:97], v[78:81]
	ds_read_b128 v[94:97], v103 offset:320
	s_nop 1
	global_load_dwordx4 v[78:81], v[108:109], off offset:320
	s_waitcnt vmcnt(11) lgkmcnt(1)
	v_mfma_f32_16x16x32_bf16 v[2:5], v[82:85], v[98:101], v[2:5]
	global_load_dwordx4 v[82:85], v[110:111], off offset:320
	s_waitcnt vmcnt(11)
	v_mfma_f32_16x16x32_bf16 v[6:9], v[86:89], v[98:101], v[6:9]
	global_load_dwordx4 v[86:89], v[112:113], off offset:320
	s_waitcnt vmcnt(11)
	v_mfma_f32_16x16x32_bf16 v[10:13], v[90:93], v[98:101], v[10:13]
	global_load_dwordx4 v[90:93], v[114:115], off offset:320
	s_waitcnt vmcnt(11)
	v_mfma_f32_16x16x32_bf16 v[14:17], v[34:37], v[98:101], v[14:17]
	global_load_dwordx4 v[34:37], v[116:117], off offset:320
	s_waitcnt vmcnt(11)
	v_mfma_f32_16x16x32_bf16 v[18:21], v[38:41], v[98:101], v[18:21]
	global_load_dwordx4 v[38:41], v[118:119], off offset:320
	s_waitcnt vmcnt(11)
	v_mfma_f32_16x16x32_bf16 v[22:25], v[42:45], v[98:101], v[22:25]
	global_load_dwordx4 v[42:45], v[120:121], off offset:320
	s_waitcnt vmcnt(11)
	v_mfma_f32_16x16x32_bf16 v[26:29], v[46:49], v[98:101], v[26:29]
	global_load_dwordx4 v[46:49], v[122:123], off offset:320
	s_waitcnt vmcnt(11)
	v_mfma_f32_16x16x32_bf16 v[30:33], v[50:53], v[98:101], v[30:33]
	global_load_dwordx4 v[50:53], v[124:125], off offset:320
	s_waitcnt vmcnt(11)
	v_mfma_f32_16x16x32_bf16 v[54:57], v[54:57], v[98:101], v[58:61]
	s_nop 2
	global_load_dwordx4 v[58:61], v[126:127], off offset:320
	s_waitcnt vmcnt(11)
	v_mfma_f32_16x16x32_bf16 v[62:65], v[62:65], v[98:101], v[66:69]
	s_nop 2
	global_load_dwordx4 v[66:69], v[128:129], off offset:320
	s_waitcnt vmcnt(11)
	v_mfma_f32_16x16x32_bf16 v[70:73], v[70:73], v[98:101], v[74:77]
	ds_read_b128 v[98:101], v103 offset:384
	s_nop 1
	global_load_dwordx4 v[74:77], v[108:109], off offset:384
	s_waitcnt vmcnt(11) lgkmcnt(1)
	v_mfma_f32_16x16x32_bf16 v[2:5], v[78:81], v[94:97], v[2:5]
	global_load_dwordx4 v[78:81], v[110:111], off offset:384
	s_waitcnt vmcnt(11)
	v_mfma_f32_16x16x32_bf16 v[6:9], v[82:85], v[94:97], v[6:9]
	global_load_dwordx4 v[82:85], v[112:113], off offset:384
	s_waitcnt vmcnt(11)
	v_mfma_f32_16x16x32_bf16 v[10:13], v[86:89], v[94:97], v[10:13]
	global_load_dwordx4 v[86:89], v[114:115], off offset:384
	s_waitcnt vmcnt(11)
	v_mfma_f32_16x16x32_bf16 v[14:17], v[90:93], v[94:97], v[14:17]
	global_load_dwordx4 v[90:93], v[116:117], off offset:384
	s_waitcnt vmcnt(11)
	v_mfma_f32_16x16x32_bf16 v[18:21], v[34:37], v[94:97], v[18:21]
	global_load_dwordx4 v[34:37], v[118:119], off offset:384
	s_waitcnt vmcnt(11)
	v_mfma_f32_16x16x32_bf16 v[22:25], v[38:41], v[94:97], v[22:25]
	global_load_dwordx4 v[38:41], v[120:121], off offset:384
	s_waitcnt vmcnt(11)
	v_mfma_f32_16x16x32_bf16 v[26:29], v[42:45], v[94:97], v[26:29]
	global_load_dwordx4 v[42:45], v[122:123], off offset:384
	s_waitcnt vmcnt(11)
	v_mfma_f32_16x16x32_bf16 v[30:33], v[46:49], v[94:97], v[30:33]
	global_load_dwordx4 v[46:49], v[124:125], off offset:384
	s_waitcnt vmcnt(11)
	v_mfma_f32_16x16x32_bf16 v[50:53], v[50:53], v[94:97], v[54:57]
	s_nop 2
	global_load_dwordx4 v[54:57], v[126:127], off offset:384
	s_waitcnt vmcnt(10)
	v_mfma_f32_16x16x32_bf16 v[66:69], v[66:69], v[94:97], v[70:73]
	s_nop 2
	global_load_dwordx4 v[70:73], v[108:109], off offset:448
	v_mfma_f32_16x16x32_bf16 v[58:61], v[58:61], v[94:97], v[62:65]
	ds_read_b128 v[94:97], v103 offset:448
	s_waitcnt vmcnt(10) lgkmcnt(1)
	v_mfma_f32_16x16x32_bf16 v[2:5], v[74:77], v[98:101], v[2:5]
	global_load_dwordx4 v[74:77], v[110:111], off offset:448
	global_load_dwordx4 v[62:65], v[128:129], off offset:384
	s_waitcnt vmcnt(11)
	v_mfma_f32_16x16x32_bf16 v[6:9], v[78:81], v[98:101], v[6:9]
	global_load_dwordx4 v[78:81], v[112:113], off offset:448
	s_waitcnt vmcnt(11)
	v_mfma_f32_16x16x32_bf16 v[10:13], v[82:85], v[98:101], v[10:13]
	global_load_dwordx4 v[82:85], v[114:115], off offset:448
	s_waitcnt vmcnt(11)
	v_mfma_f32_16x16x32_bf16 v[14:17], v[86:89], v[98:101], v[14:17]
	global_load_dwordx4 v[86:89], v[116:117], off offset:448
	s_waitcnt vmcnt(11)
	v_mfma_f32_16x16x32_bf16 v[18:21], v[90:93], v[98:101], v[18:21]
	global_load_dwordx4 v[90:93], v[118:119], off offset:448
	s_waitcnt vmcnt(11)
	v_mfma_f32_16x16x32_bf16 v[22:25], v[34:37], v[98:101], v[22:25]
	global_load_dwordx4 v[34:37], v[120:121], off offset:448
	s_waitcnt vmcnt(11)
	v_mfma_f32_16x16x32_bf16 v[26:29], v[38:41], v[98:101], v[26:29]
	global_load_dwordx4 v[38:41], v[122:123], off offset:448
	s_waitcnt vmcnt(11)
	v_mfma_f32_16x16x32_bf16 v[30:33], v[42:45], v[98:101], v[30:33]
	global_load_dwordx4 v[42:45], v[124:125], off offset:448
	s_waitcnt vmcnt(11)
	v_mfma_f32_16x16x32_bf16 v[46:49], v[46:49], v[98:101], v[50:53]
	s_nop 2
	global_load_dwordx4 v[50:53], v[126:127], off offset:448
	s_waitcnt vmcnt(11)
	v_mfma_f32_16x16x32_bf16 v[54:57], v[54:57], v[98:101], v[58:61]
	s_nop 2
	global_load_dwordx4 v[58:61], v[128:129], off offset:448
	s_waitcnt vmcnt(11) lgkmcnt(0)
	v_mfma_f32_16x16x32_bf16 v[2:5], v[70:73], v[94:97], v[2:5]
	s_waitcnt vmcnt(10)
	v_mfma_f32_16x16x32_bf16 v[6:9], v[74:77], v[94:97], v[6:9]
	s_waitcnt vmcnt(8)
	v_mfma_f32_16x16x32_bf16 v[10:13], v[78:81], v[94:97], v[10:13]
	s_waitcnt vmcnt(7)
	v_mfma_f32_16x16x32_bf16 v[14:17], v[82:85], v[94:97], v[14:17]
	s_waitcnt vmcnt(4)
	v_mfma_f32_16x16x32_bf16 v[26:29], v[34:37], v[94:97], v[26:29]
	v_lshl_add_u32 v34, v1, 4, s0
	ds_write_b128 v34, v[2:5]
	ds_write_b128 v34, v[6:9] offset:1024
	s_nop 0
	ds_write_b128 v34, v[10:13] offset:2048
	s_nop 0
	ds_write_b128 v34, v[14:17] offset:3072
	v_mfma_f32_16x16x32_bf16 v[62:65], v[62:65], v[98:101], v[66:69]
	v_mfma_f32_16x16x32_bf16 v[18:21], v[86:89], v[94:97], v[18:21]
	s_waitcnt vmcnt(3)
	v_mfma_f32_16x16x32_bf16 v[2:5], v[38:41], v[94:97], v[30:33]
	v_mfma_f32_16x16x32_bf16 v[22:25], v[90:93], v[94:97], v[22:25]
	s_nop 4
	ds_write_b128 v34, v[18:21] offset:4096
	s_nop 1
	ds_write_b128 v34, v[22:25] offset:5120
	ds_write_b128 v34, v[26:29] offset:6144
	s_waitcnt vmcnt(2)
	v_mfma_f32_16x16x32_bf16 v[6:9], v[42:45], v[94:97], v[46:49]
	s_waitcnt vmcnt(1)
	v_mfma_f32_16x16x32_bf16 v[10:13], v[50:53], v[94:97], v[54:57]
	ds_write_b128 v34, v[2:5] offset:7168
	s_nop 4
	ds_write_b128 v34, v[6:9] offset:8192
	s_nop 0
	ds_write_b128 v34, v[10:13] offset:9216
	s_waitcnt vmcnt(0)
	v_mfma_f32_16x16x32_bf16 v[2:5], v[58:61], v[94:97], v[62:65]
	s_nop 7
	ds_write_b128 v34, v[2:5] offset:10240
	s_waitcnt lgkmcnt(0)
	s_barrier
	s_cbranch_scc1 .LBB0_1075
	v_or_b32_e32 v2, s9, v147
	v_mul_u32_u24_e32 v2, 0xb00, v2
	v_bfe_u32 v6, v146, 4, 2
	v_lshlrev_b32_e32 v2, 1, v2
	v_mov_b32_e32 v3, 0
	v_lshl_add_u64 v[4:5], s[36:37], 0, v[2:3]
	v_lshlrev_b32_e32 v2, 3, v6
	v_lshl_add_u64 v[2:3], v[4:5], 0, v[2:3]
	s_mov_b64 s[0:1], 0x5800000
	v_lshl_add_u64 v[2:3], v[2:3], 0, s[0:1]
	s_mul_i32 s0, s7, 0xb0
	s_lshl_b32 s1, s6, 4
	s_add_i32 s0, s0, s1
	s_lshl_b32 s1, s6, 10
	s_add_i32 s1, s1, 0
	s_add_i32 s2, s6, -8
	v_lshl_add_u32 v1, v1, 4, s1
